# RWKV prep stage: the 8 tokens' second wave-sum (bonus scalar) reduced together with one unmasked write pair, per-token reduction chains and masked writes removed
# baseline (speedup 1.0000x reference)
; __device__ __forceinline__ void phase_rwkv(KP P, int l_, unsigned char* shm) {
;     ...
;                 if (c + 1 < NC) { RW_PREP(c + 1); if (c + 2 < NC) RW_LOAD(c + 2); }
.Lrw_nopack:
	s_andn2_b64 vcc, exec, s[72:73]
	v_mov_b32_e32 v0, v176
	v_mov_b32_e32 v1, v214
	v_mov_b32_e32 v2, v219
	v_mov_b32_e32 v3, v177
	v_mov_b32_e32 v9, v190
	v_mov_b32_e32 v10, v191
	v_mov_b32_e32 v11, v192
	v_mov_b32_e32 v21, v193
	v_mov_b32_e32 v28, v194
	v_mov_b32_e32 v35, v195
	v_mov_b32_e32 v38, v196
	v_mov_b32_e32 v4, v197
	v_mov_b32_e32 v8, v198
	v_mov_b32_e32 v12, v199
	v_mov_b32_e32 v13, v200
	v_mov_b32_e32 v30, v201
	v_mov_b32_e32 v31, v202
	v_mov_b32_e32 v33, v203
	v_mov_b32_e32 v37, v204
	v_mov_b32_e32 v6, v205
	v_mov_b32_e32 v7, v206
	v_mov_b32_e32 v14, v207
	v_mov_b32_e32 v15, v208
	v_mov_b32_e32 v32, v209
	v_mov_b32_e32 v34, v210
	v_mov_b32_e32 v36, v211
	v_mov_b32_e32 v39, v212
	s_cbranch_vccnz .LBB0_2513
	v_and_b32_e32 v2, 0xffff0000, v222
	v_lshlrev_b32_e32 v3, 16, v222
	v_sub_f32_e32 v3, v3, v2
	v_fma_f32 v3, v245, v3, v2
	v_mul_f32_e32 v9, v247, v3
	v_mul_f32_e32 v10, v9, v9
	s_add_i32 s0, s42, 1
	s_and_b32 s1, s0, 1
	v_mov_b32_dpp v10, v10 quad_perm:[1,0,3,2] row_mask:0xf bank_mask:0xf bound_ctrl:1
	v_fmac_f32_e32 v10, v9, v9
	s_mul_i32 s43, s1, 0xa000
	s_add_i32 s52, s43, 0
	v_add_f32_dpp v10, v10, v10 quad_perm:[2,3,0,1] row_mask:0xf bank_mask:0xf bound_ctrl:1
	s_mul_hi_u32 s43, s0, 0xaaaaaaab
	v_lshlrev_b32_e32 v8, 16, v197
	v_add_f32_dpp v10, v10, v10 row_half_mirror row_mask:0xf bank_mask:0xf bound_ctrl:1
	v_mov_b32_e32 v11, 0
	s_lshr_b32 s43, s43, 1
	v_add_f32_dpp v10, v10, v10 row_mirror row_mask:0xf bank_mask:0xf bound_ctrl:1
	v_add_f32_e32 v8, v251, v8
	s_mul_i32 s43, s43, 3
	v_mov_b32_dpp v11, v10 row_bcast:15 row_mask:0xa bank_mask:0xf
	v_mul_f32_e32 v8, 0xbfb8aa3b, v8
	v_add_f32_e32 v10, v10, v11
	v_mov_b32_e32 v11, 0
	s_sub_i32 s0, s0, s43
	v_exp_f32_e32 v8, v8
	v_mov_b32_dpp v11, v10 row_bcast:31 row_mask:0xc bank_mask:0xf
	s_lshl_b32 s43, s0, 13
	s_lshl_b32 s0, s0, 7
	v_add_f32_e32 v10, v10, v11
	s_add_i32 vcc_lo, s43, 0
	s_add_i32 s43, s0, 0
	v_readlane_b32 s0, v10, 63
	v_add_f32_e32 v8, 1.0, v8
	v_rcp_f32_e32 v8, v8
	v_max_f32_e64 v10, s0, s0
	v_max_f32_e32 v10, 0x179abe15, v10
	v_rsq_f32_e32 v10, v10
	v_lshlrev_b32_e32 v6, 16, v205
	v_add_f32_e32 v6, v250, v6
	v_mul_f32_e32 v6, 0xbfb8aa3b, v6
	v_and_b32_e32 v4, 0xffff0000, v221
	v_lshlrev_b32_e32 v1, 16, v221
	v_exp_f32_e32 v6, v6
	v_mul_f32_e32 v9, v9, v10
	v_add_f32_e32 v10, -1.0, v8
	v_sub_f32_e32 v1, v1, v4
	v_fma_f32 v10, v248, v10, 1.0
	v_fma_f32 v1, v244, v1, v4
	v_mul_f32_e32 v3, v10, v3
	v_mul_f32_e32 v10, v1, v3
	v_add_f32_e32 v6, 1.0, v6
	v_mul_f32_e32 v66, v249, v10
	v_rcp_f32_e32 v6, v6
	s_lshl_b32 s1, s1, 13
	v_mul_f32_e32 v6, 0xbf1b4598, v6
	v_mul_f32_e32 v6, 0x3fb8aa3b, v6
	v_exp_f32_e32 v6, v6
	v_and_b32_e32 v0, 0xffff0000, v215
	v_lshlrev_b32_e32 v7, 16, v215
	s_add_i32 vcc_lo, vcc_lo, 0x14000
	s_add_i32 vcc_hi, s1, 0
	v_sub_f32_e32 v7, v7, v0
	s_add_i32 vcc_hi, vcc_hi, 0x1a000
	v_fma_f32 v7, v246, v7, v0
	v_add_u32_e32 v10, s52, v124
	ds_write2st64_b32 v10, v6, v9 offset1:32
	v_mul_f32_e32 v6, v8, v9
	ds_write2st64_b32 v10, v6, v3 offset0:64 offset1:96
	ds_write_b32 v10, v1 offset:32768
	v_add_u32_e32 v1, vcc_lo, v124
	s_add_i32 s43, s43, 0x22000
	ds_write_b32 v1, v7
	v_lshlrev_b32_e32 v1, 16, v177
	v_add_u32_e32 v3, vcc_hi, v124
	ds_write_b32 v3, v1
	v_lshlrev_b32_e32 v3, 16, v226
	v_sub_f32_e32 v2, v2, v3
	v_fma_f32 v2, v245, v2, v3
	v_mul_f32_e32 v9, v247, v2
	v_mul_f32_e32 v10, v9, v9
	v_lshlrev_b32_e32 v8, 16, v198
	v_mov_b32_e32 v11, 0
	v_mov_b32_dpp v10, v10 quad_perm:[1,0,3,2] row_mask:0xf bank_mask:0xf bound_ctrl:1
	v_fmac_f32_e32 v10, v9, v9
	v_add_f32_e32 v8, v251, v8
	v_mul_f32_e32 v8, 0xbfb8aa3b, v8
	v_add_f32_dpp v10, v10, v10 quad_perm:[2,3,0,1] row_mask:0xf bank_mask:0xf bound_ctrl:1
	v_exp_f32_e32 v8, v8
	v_lshlrev_b32_e32 v7, 16, v206
	v_add_f32_dpp v10, v10, v10 row_half_mirror row_mask:0xf bank_mask:0xf bound_ctrl:1
	v_add_f32_e32 v7, v250, v7
	v_add_f32_e32 v8, 1.0, v8
	v_add_f32_dpp v10, v10, v10 row_mirror row_mask:0xf bank_mask:0xf bound_ctrl:1
	v_rcp_f32_e32 v8, v8
	v_mul_f32_e32 v7, 0xbfb8aa3b, v7
	v_mov_b32_dpp v11, v10 row_bcast:15 row_mask:0xa bank_mask:0xf
	v_add_f32_e32 v10, v10, v11
	v_mov_b32_e32 v11, 0
	v_lshlrev_b32_e32 v6, 16, v223
	v_exp_f32_e32 v7, v7
	v_mov_b32_dpp v11, v10 row_bcast:31 row_mask:0xc bank_mask:0xf
	v_add_f32_e32 v10, v10, v11
	v_sub_f32_e32 v4, v4, v6
	v_readlane_b32 s0, v10, 63
	v_fma_f32 v4, v244, v4, v6
	v_add_f32_e32 v7, 1.0, v7
	v_max_f32_e64 v10, s0, s0
	v_max_f32_e32 v10, 0x179abe15, v10
	v_rsq_f32_e32 v10, v10
	v_rcp_f32_e32 v7, v7
	v_lshlrev_b32_e32 v1, 16, v216
	v_sub_f32_e32 v0, v0, v1
	v_mul_f32_e32 v9, v9, v10
	v_add_f32_e32 v10, -1.0, v8
	v_fma_f32 v10, v248, v10, 1.0
	v_mul_f32_e32 v2, v10, v2
	v_mul_f32_e32 v10, v4, v2
	v_mul_f32_e32 v67, v249, v10
	v_mul_f32_e32 v7, 0xbf1b4598, v7
	v_mul_f32_e32 v7, 0x3fb8aa3b, v7
	v_exp_f32_e32 v7, v7
	v_fma_f32 v0, v246, v0, v1
	v_add_u32_e32 v10, s52, v128
	ds_write2st64_b32 v10, v7, v9 offset1:32
	v_mul_f32_e32 v7, v8, v9
	ds_write2st64_b32 v10, v7, v2 offset0:64 offset1:96
	ds_write_b32 v10, v4 offset:32768
	v_add_u32_e32 v2, vcc_lo, v128
	ds_write_b32 v2, v0
	v_lshlrev_b32_e32 v0, 16, v190
	v_add_u32_e32 v2, vcc_hi, v128
	ds_write_b32 v2, v0
	v_and_b32_e32 v2, 0xffff0000, v226
	v_sub_f32_e32 v3, v3, v2
	v_fma_f32 v3, v245, v3, v2
	v_mul_f32_e32 v9, v247, v3
	v_mul_f32_e32 v10, v9, v9
	v_lshlrev_b32_e32 v8, 16, v199
	v_mov_b32_e32 v11, 0
	v_mov_b32_dpp v10, v10 quad_perm:[1,0,3,2] row_mask:0xf bank_mask:0xf bound_ctrl:1
	v_fmac_f32_e32 v10, v9, v9
	v_add_f32_e32 v8, v251, v8
	v_mul_f32_e32 v8, 0xbfb8aa3b, v8
	v_add_f32_dpp v10, v10, v10 quad_perm:[2,3,0,1] row_mask:0xf bank_mask:0xf bound_ctrl:1
	v_exp_f32_e32 v8, v8
	v_lshlrev_b32_e32 v7, 16, v207
	v_add_f32_dpp v10, v10, v10 row_half_mirror row_mask:0xf bank_mask:0xf bound_ctrl:1
	v_add_f32_e32 v7, v250, v7
	v_add_f32_e32 v8, 1.0, v8
	v_add_f32_dpp v10, v10, v10 row_mirror row_mask:0xf bank_mask:0xf bound_ctrl:1
	v_rcp_f32_e32 v8, v8
	v_mul_f32_e32 v7, 0xbfb8aa3b, v7
	v_mov_b32_dpp v11, v10 row_bcast:15 row_mask:0xa bank_mask:0xf
	v_add_f32_e32 v10, v10, v11
	v_mov_b32_e32 v11, 0
	v_and_b32_e32 v4, 0xffff0000, v223
	v_exp_f32_e32 v7, v7
	v_mov_b32_dpp v11, v10 row_bcast:31 row_mask:0xc bank_mask:0xf
	v_add_f32_e32 v10, v10, v11
	v_sub_f32_e32 v6, v6, v4
	v_readlane_b32 s0, v10, 63
	v_fma_f32 v6, v244, v6, v4
	v_add_f32_e32 v7, 1.0, v7
	v_max_f32_e64 v10, s0, s0
	v_max_f32_e32 v10, 0x179abe15, v10
	v_rsq_f32_e32 v10, v10
	v_rcp_f32_e32 v7, v7
	v_and_b32_e32 v0, 0xffff0000, v216
	v_sub_f32_e32 v1, v1, v0
	v_mul_f32_e32 v9, v9, v10
	v_add_f32_e32 v10, -1.0, v8
	v_fma_f32 v10, v248, v10, 1.0
	v_mul_f32_e32 v3, v10, v3
	v_mul_f32_e32 v10, v6, v3
	v_mul_f32_e32 v68, v249, v10
	v_mul_f32_e32 v7, 0xbf1b4598, v7
	v_mul_f32_e32 v7, 0x3fb8aa3b, v7
	v_exp_f32_e32 v7, v7
	v_fma_f32 v1, v246, v1, v0
	v_add_u32_e32 v10, s52, v132
	ds_write2st64_b32 v10, v7, v9 offset1:32
	v_mul_f32_e32 v7, v8, v9
	ds_write2st64_b32 v10, v7, v3 offset0:64 offset1:96
	ds_write_b32 v10, v6 offset:32768
	v_add_u32_e32 v3, vcc_lo, v132
	ds_write_b32 v3, v1
	v_lshlrev_b32_e32 v1, 16, v191
	v_add_u32_e32 v3, vcc_hi, v132
	ds_write_b32 v3, v1
	v_lshlrev_b32_e32 v3, 16, v227
	v_sub_f32_e32 v2, v2, v3
	v_fma_f32 v2, v245, v2, v3
	v_mul_f32_e32 v9, v247, v2
	v_mul_f32_e32 v10, v9, v9
	v_lshlrev_b32_e32 v8, 16, v200
	v_mov_b32_e32 v11, 0
	v_mov_b32_dpp v10, v10 quad_perm:[1,0,3,2] row_mask:0xf bank_mask:0xf bound_ctrl:1
	v_fmac_f32_e32 v10, v9, v9
	v_add_f32_e32 v8, v251, v8
	v_mul_f32_e32 v8, 0xbfb8aa3b, v8
	v_add_f32_dpp v10, v10, v10 quad_perm:[2,3,0,1] row_mask:0xf bank_mask:0xf bound_ctrl:1
	v_exp_f32_e32 v8, v8
	v_lshlrev_b32_e32 v7, 16, v208
	v_add_f32_dpp v10, v10, v10 row_half_mirror row_mask:0xf bank_mask:0xf bound_ctrl:1
	v_add_f32_e32 v7, v250, v7
	v_add_f32_e32 v8, 1.0, v8
	v_add_f32_dpp v10, v10, v10 row_mirror row_mask:0xf bank_mask:0xf bound_ctrl:1
	v_rcp_f32_e32 v8, v8
	v_mul_f32_e32 v7, 0xbfb8aa3b, v7
	v_mov_b32_dpp v11, v10 row_bcast:15 row_mask:0xa bank_mask:0xf
	v_add_f32_e32 v10, v10, v11
	v_mov_b32_e32 v11, 0
	v_lshlrev_b32_e32 v6, 16, v224
	v_exp_f32_e32 v7, v7
	v_mov_b32_dpp v11, v10 row_bcast:31 row_mask:0xc bank_mask:0xf
	v_add_f32_e32 v10, v10, v11
	v_sub_f32_e32 v4, v4, v6
	v_readlane_b32 s0, v10, 63
	v_fma_f32 v4, v244, v4, v6
	v_add_f32_e32 v7, 1.0, v7
	v_max_f32_e64 v10, s0, s0
	v_max_f32_e32 v10, 0x179abe15, v10
	v_rsq_f32_e32 v10, v10
	v_rcp_f32_e32 v7, v7
	v_lshlrev_b32_e32 v1, 16, v217
	v_sub_f32_e32 v0, v0, v1
	v_mul_f32_e32 v9, v9, v10
	v_add_f32_e32 v10, -1.0, v8
	v_fma_f32 v10, v248, v10, 1.0
	v_mul_f32_e32 v2, v10, v2
	v_mul_f32_e32 v10, v4, v2
	v_mul_f32_e32 v69, v249, v10
	v_mul_f32_e32 v7, 0xbf1b4598, v7
	v_mul_f32_e32 v7, 0x3fb8aa3b, v7
	v_exp_f32_e32 v7, v7
	v_fma_f32 v0, v246, v0, v1
	v_add_u32_e32 v10, s52, v136
	ds_write2st64_b32 v10, v7, v9 offset1:32
	v_mul_f32_e32 v7, v8, v9
	ds_write2st64_b32 v10, v7, v2 offset0:64 offset1:96
	ds_write_b32 v10, v4 offset:32768
	v_add_u32_e32 v2, vcc_lo, v136
	ds_write_b32 v2, v0
	v_lshlrev_b32_e32 v0, 16, v192
	v_add_u32_e32 v2, vcc_hi, v136
	ds_write_b32 v2, v0
	v_and_b32_e32 v2, 0xffff0000, v227
	v_sub_f32_e32 v3, v3, v2
	v_fma_f32 v3, v245, v3, v2
	v_mul_f32_e32 v9, v247, v3
	v_mul_f32_e32 v10, v9, v9
	v_lshlrev_b32_e32 v8, 16, v201
	v_mov_b32_e32 v11, 0
	v_mov_b32_dpp v10, v10 quad_perm:[1,0,3,2] row_mask:0xf bank_mask:0xf bound_ctrl:1
	v_fmac_f32_e32 v10, v9, v9
	v_add_f32_e32 v8, v251, v8
	v_mul_f32_e32 v8, 0xbfb8aa3b, v8
	v_add_f32_dpp v10, v10, v10 quad_perm:[2,3,0,1] row_mask:0xf bank_mask:0xf bound_ctrl:1
	v_exp_f32_e32 v8, v8
	v_lshlrev_b32_e32 v7, 16, v209
	v_add_f32_dpp v10, v10, v10 row_half_mirror row_mask:0xf bank_mask:0xf bound_ctrl:1
	v_add_f32_e32 v7, v250, v7
	v_add_f32_e32 v8, 1.0, v8
	v_add_f32_dpp v10, v10, v10 row_mirror row_mask:0xf bank_mask:0xf bound_ctrl:1
	v_rcp_f32_e32 v8, v8
	v_mul_f32_e32 v7, 0xbfb8aa3b, v7
	v_mov_b32_dpp v11, v10 row_bcast:15 row_mask:0xa bank_mask:0xf
	v_add_f32_e32 v10, v10, v11
	v_mov_b32_e32 v11, 0
	v_and_b32_e32 v4, 0xffff0000, v224
	v_exp_f32_e32 v7, v7
	v_mov_b32_dpp v11, v10 row_bcast:31 row_mask:0xc bank_mask:0xf
	v_add_f32_e32 v10, v10, v11
	v_sub_f32_e32 v6, v6, v4
	v_readlane_b32 s0, v10, 63
	v_fma_f32 v6, v244, v6, v4
	v_add_f32_e32 v7, 1.0, v7
	v_max_f32_e64 v10, s0, s0
	v_max_f32_e32 v10, 0x179abe15, v10
	v_rsq_f32_e32 v10, v10
	v_rcp_f32_e32 v7, v7
	v_and_b32_e32 v0, 0xffff0000, v217
	v_sub_f32_e32 v1, v1, v0
	v_mul_f32_e32 v9, v9, v10
	v_add_f32_e32 v10, -1.0, v8
	v_fma_f32 v10, v248, v10, 1.0
	v_mul_f32_e32 v3, v10, v3
	v_mul_f32_e32 v10, v6, v3
	v_mul_f32_e32 v70, v249, v10
	v_mul_f32_e32 v7, 0xbf1b4598, v7
	v_mul_f32_e32 v7, 0x3fb8aa3b, v7
	v_exp_f32_e32 v7, v7
	v_fma_f32 v1, v246, v1, v0
	v_add_u32_e32 v10, s52, v140
	ds_write2st64_b32 v10, v7, v9 offset1:32
	v_mul_f32_e32 v7, v8, v9
	ds_write2st64_b32 v10, v7, v3 offset0:64 offset1:96
	ds_write_b32 v10, v6 offset:32768
	v_add_u32_e32 v3, vcc_lo, v140
	ds_write_b32 v3, v1
	v_lshlrev_b32_e32 v1, 16, v193
	v_add_u32_e32 v3, vcc_hi, v140
	ds_write_b32 v3, v1
	v_lshlrev_b32_e32 v3, 16, v242
	v_sub_f32_e32 v2, v2, v3
	v_fma_f32 v2, v245, v2, v3
	v_mul_f32_e32 v9, v247, v2
	v_mul_f32_e32 v10, v9, v9
	v_lshlrev_b32_e32 v8, 16, v202
	v_mov_b32_e32 v11, 0
	v_mov_b32_dpp v10, v10 quad_perm:[1,0,3,2] row_mask:0xf bank_mask:0xf bound_ctrl:1
	v_fmac_f32_e32 v10, v9, v9
	v_add_f32_e32 v8, v251, v8
	v_mul_f32_e32 v8, 0xbfb8aa3b, v8
	v_add_f32_dpp v10, v10, v10 quad_perm:[2,3,0,1] row_mask:0xf bank_mask:0xf bound_ctrl:1
	v_exp_f32_e32 v8, v8
	v_lshlrev_b32_e32 v7, 16, v210
	v_add_f32_dpp v10, v10, v10 row_half_mirror row_mask:0xf bank_mask:0xf bound_ctrl:1
	v_add_f32_e32 v7, v250, v7
	v_add_f32_e32 v8, 1.0, v8
	v_add_f32_dpp v10, v10, v10 row_mirror row_mask:0xf bank_mask:0xf bound_ctrl:1
	v_rcp_f32_e32 v8, v8
	v_mul_f32_e32 v7, 0xbfb8aa3b, v7
	v_mov_b32_dpp v11, v10 row_bcast:15 row_mask:0xa bank_mask:0xf
	v_add_f32_e32 v10, v10, v11
	v_mov_b32_e32 v11, 0
	v_lshlrev_b32_e32 v6, 16, v225
	v_exp_f32_e32 v7, v7
	v_mov_b32_dpp v11, v10 row_bcast:31 row_mask:0xc bank_mask:0xf
	v_add_f32_e32 v10, v10, v11
	v_sub_f32_e32 v4, v4, v6
	v_readlane_b32 s0, v10, 63
	v_fma_f32 v4, v244, v4, v6
	v_add_f32_e32 v7, 1.0, v7
	v_max_f32_e64 v10, s0, s0
	v_max_f32_e32 v10, 0x179abe15, v10
	v_rsq_f32_e32 v10, v10
	v_rcp_f32_e32 v7, v7
	v_lshlrev_b32_e32 v1, 16, v218
	v_sub_f32_e32 v0, v0, v1
	v_mul_f32_e32 v9, v9, v10
	v_add_f32_e32 v10, -1.0, v8
	v_fma_f32 v10, v248, v10, 1.0
	v_mul_f32_e32 v2, v10, v2
	v_mul_f32_e32 v10, v4, v2
	v_mul_f32_e32 v71, v249, v10
	v_mul_f32_e32 v7, 0xbf1b4598, v7
	v_mul_f32_e32 v7, 0x3fb8aa3b, v7
	v_exp_f32_e32 v7, v7
	v_fma_f32 v0, v246, v0, v1
	v_add_u32_e32 v10, s52, v144
	ds_write2st64_b32 v10, v7, v9 offset1:32
	v_mul_f32_e32 v7, v8, v9
	ds_write2st64_b32 v10, v7, v2 offset0:64 offset1:96
	ds_write_b32 v10, v4 offset:32768
	v_add_u32_e32 v2, vcc_lo, v144
	ds_write_b32 v2, v0
	v_lshlrev_b32_e32 v0, 16, v194
	v_add_u32_e32 v2, vcc_hi, v144
	ds_write_b32 v2, v0
	v_and_b32_e32 v2, 0xffff0000, v242
	v_sub_f32_e32 v3, v3, v2
	v_fma_f32 v3, v245, v3, v2
	v_mul_f32_e32 v9, v247, v3
	v_mul_f32_e32 v10, v9, v9
	v_lshlrev_b32_e32 v8, 16, v203
	v_mov_b32_e32 v11, 0
	v_mov_b32_dpp v10, v10 quad_perm:[1,0,3,2] row_mask:0xf bank_mask:0xf bound_ctrl:1
	v_fmac_f32_e32 v10, v9, v9
	v_add_f32_e32 v8, v251, v8
	v_mul_f32_e32 v8, 0xbfb8aa3b, v8
	v_add_f32_dpp v10, v10, v10 quad_perm:[2,3,0,1] row_mask:0xf bank_mask:0xf bound_ctrl:1
	v_exp_f32_e32 v8, v8
	v_lshlrev_b32_e32 v7, 16, v211
	v_add_f32_dpp v10, v10, v10 row_half_mirror row_mask:0xf bank_mask:0xf bound_ctrl:1
	v_add_f32_e32 v7, v250, v7
	v_add_f32_e32 v8, 1.0, v8
	v_add_f32_dpp v10, v10, v10 row_mirror row_mask:0xf bank_mask:0xf bound_ctrl:1
	v_rcp_f32_e32 v8, v8
	v_mul_f32_e32 v7, 0xbfb8aa3b, v7
	v_mov_b32_dpp v11, v10 row_bcast:15 row_mask:0xa bank_mask:0xf
	v_add_f32_e32 v10, v10, v11
	v_mov_b32_e32 v11, 0
	v_and_b32_e32 v4, 0xffff0000, v225
	v_exp_f32_e32 v7, v7
	v_mov_b32_dpp v11, v10 row_bcast:31 row_mask:0xc bank_mask:0xf
	v_add_f32_e32 v10, v10, v11
	v_sub_f32_e32 v6, v6, v4
	v_readlane_b32 s0, v10, 63
	v_fma_f32 v6, v244, v6, v4
	v_add_f32_e32 v7, 1.0, v7
	v_max_f32_e64 v10, s0, s0
	v_max_f32_e32 v10, 0x179abe15, v10
	v_rsq_f32_e32 v10, v10
	v_rcp_f32_e32 v7, v7
	v_and_b32_e32 v0, 0xffff0000, v218
	v_sub_f32_e32 v1, v1, v0
	v_mul_f32_e32 v9, v9, v10
	v_add_f32_e32 v10, -1.0, v8
	v_fma_f32 v10, v248, v10, 1.0
	v_mul_f32_e32 v3, v10, v3
	v_mul_f32_e32 v10, v6, v3
	v_mul_f32_e32 v72, v249, v10
	v_mul_f32_e32 v7, 0xbf1b4598, v7
	v_mul_f32_e32 v7, 0x3fb8aa3b, v7
	v_exp_f32_e32 v7, v7
	v_fma_f32 v1, v246, v1, v0
	v_add_u32_e32 v10, s52, v148
	ds_write2st64_b32 v10, v7, v9 offset1:32
	v_mul_f32_e32 v7, v8, v9
	ds_write2st64_b32 v10, v7, v3 offset0:64 offset1:96
	ds_write_b32 v10, v6 offset:32768
	v_add_u32_e32 v3, vcc_lo, v148
	ds_write_b32 v3, v1
	v_lshlrev_b32_e32 v1, 16, v195
	v_add_u32_e32 v3, vcc_hi, v148
	ds_write_b32 v3, v1
	v_lshlrev_b32_e32 v7, 16, v212
	v_add_f32_e32 v7, v250, v7
	v_mul_f32_e32 v7, 0xbfb8aa3b, v7
	v_lshlrev_b32_e32 v1, 16, v176
	v_exp_f32_e32 v7, v7
	v_sub_f32_e32 v4, v4, v1
	v_lshlrev_b32_e32 v3, 16, v214
	v_fmac_f32_e32 v1, v244, v4
	v_lshlrev_b32_e32 v4, 16, v204
	v_sub_f32_e32 v2, v2, v3
	v_add_f32_e32 v4, v251, v4
	v_fmac_f32_e32 v3, v245, v2
	v_add_f32_e32 v2, 1.0, v7
	v_mul_f32_e32 v4, 0xbfb8aa3b, v4
	v_rcp_f32_e32 v2, v2
	v_exp_f32_e32 v4, v4
	v_lshlrev_b32_e32 v6, 16, v219
	v_sub_f32_e32 v0, v0, v6
	v_fmac_f32_e32 v6, v246, v0
	v_mul_f32_e32 v0, 0xbf1b4598, v2
	v_add_f32_e32 v2, 1.0, v4
	v_mul_f32_e32 v4, v247, v3
	v_mul_f32_e32 v7, v4, v4
	v_mov_b32_e32 v8, 0
	v_rcp_f32_e32 v2, v2
	v_mov_b32_dpp v7, v7 quad_perm:[1,0,3,2] row_mask:0xf bank_mask:0xf bound_ctrl:1
	v_fmac_f32_e32 v7, v4, v4
	v_mul_f32_e32 v0, 0x3fb8aa3b, v0
	v_exp_f32_e32 v0, v0
	v_add_f32_dpp v7, v7, v7 quad_perm:[2,3,0,1] row_mask:0xf bank_mask:0xf bound_ctrl:1
	s_nop 1
	v_add_f32_dpp v7, v7, v7 row_half_mirror row_mask:0xf bank_mask:0xf bound_ctrl:1
	s_nop 1
	v_add_f32_dpp v7, v7, v7 row_mirror row_mask:0xf bank_mask:0xf bound_ctrl:1
	s_nop 1
	v_mov_b32_dpp v8, v7 row_bcast:15 row_mask:0xa bank_mask:0xf
	v_add_f32_e32 v7, v7, v8
	v_mov_b32_e32 v8, 0
	s_nop 1
	v_mov_b32_dpp v8, v7 row_bcast:31 row_mask:0xc bank_mask:0xf
	v_add_f32_e32 v7, v7, v8
	s_nop 0
	v_readlane_b32 s0, v7, 63
	s_nop 1
	v_max_f32_e64 v7, s0, s0
	v_max_f32_e32 v7, 0x179abe15, v7
	v_rsq_f32_e32 v7, v7
	s_nop 0
	v_mul_f32_e32 v4, v4, v7
	v_add_f32_e32 v7, -1.0, v2
	v_fma_f32 v7, v248, v7, 1.0
	v_mul_f32_e32 v3, v7, v3
	v_mul_f32_e32 v7, v1, v3
	v_mul_f32_e32 v73, v249, v7
	v_add_u32_e32 v7, s52, v152
	ds_write2st64_b32 v7, v0, v4 offset1:32
	v_mul_f32_e32 v0, v2, v4
	ds_write2st64_b32 v7, v0, v3 offset0:64 offset1:96
	ds_write_b32 v7, v1 offset:32768
	v_add_u32_e32 v0, vcc_lo, v152
	ds_write_b32 v0, v6
	v_lshlrev_b32_e32 v0, 16, v196
	v_add_u32_e32 v1, vcc_hi, v152
	ds_write_b32 v1, v0
	s_mov_b32 s98, 0xaaaaaaaa
	s_mov_b32 s99, 0xaaaaaaaa
	s_mov_b32 s100, 0xcccccccc
	s_mov_b32 s101, 0xcccccccc
	v_cndmask_b32_e64 v115, v67, v66, s[98:99]
	v_cndmask_b32_e64 v117, v69, v68, s[98:99]
	v_cndmask_b32_e64 v119, v71, v70, s[98:99]
	v_cndmask_b32_e64 v121, v73, v72, s[98:99]
	v_cndmask_b32_e64 v114, v66, v67, s[98:99]
	v_cndmask_b32_e64 v116, v68, v69, s[98:99]
	v_cndmask_b32_e64 v118, v70, v71, s[98:99]
	v_cndmask_b32_e64 v120, v72, v73, s[98:99]
	v_add_f32_dpp v114, v115, v114 quad_perm:[1,0,3,2] row_mask:0xf bank_mask:0xf bound_ctrl:1
	v_add_f32_dpp v116, v117, v116 quad_perm:[1,0,3,2] row_mask:0xf bank_mask:0xf bound_ctrl:1
	v_add_f32_dpp v118, v119, v118 quad_perm:[1,0,3,2] row_mask:0xf bank_mask:0xf bound_ctrl:1
	v_add_f32_dpp v120, v121, v120 quad_perm:[1,0,3,2] row_mask:0xf bank_mask:0xf bound_ctrl:1
	v_cndmask_b32_e64 v115, v116, v114, s[100:101]
	v_cndmask_b32_e64 v119, v120, v118, s[100:101]
	v_cndmask_b32_e64 v114, v114, v116, s[100:101]
	v_cndmask_b32_e64 v118, v118, v120, s[100:101]
	v_add_f32_dpp v114, v115, v114 quad_perm:[2,3,0,1] row_mask:0xf bank_mask:0xf bound_ctrl:1
	v_add_f32_dpp v118, v119, v118 quad_perm:[2,3,0,1] row_mask:0xf bank_mask:0xf bound_ctrl:1
	s_nop 0
	v_add_f32_dpp v114, v114, v114 row_ror:4 row_mask:0xf bank_mask:0xf
	v_add_f32_dpp v118, v118, v118 row_ror:4 row_mask:0xf bank_mask:0xf
	s_nop 0
	v_add_f32_dpp v114, v114, v114 row_ror:8 row_mask:0xf bank_mask:0xf
	v_add_f32_dpp v118, v118, v118 row_ror:8 row_mask:0xf bank_mask:0xf
	v_mov_b32_e32 v115, v114
	v_mov_b32_e32 v119, v118
	s_nop 1
	v_permlane16_swap_b32_e32 v115, v114
	v_permlane16_swap_b32_e32 v119, v118
	v_add_f32_e32 v114, v114, v115
	v_add_f32_e32 v118, v118, v119
	v_mov_b32_e32 v115, v114
	v_mov_b32_e32 v119, v118
	s_nop 1
	v_permlane32_swap_b32_e32 v115, v114
	v_permlane32_swap_b32_e32 v119, v118
	v_add_f32_e32 v114, v114, v115
	v_add_f32_e32 v118, v118, v119
	s_nop 0
	v_and_b32_e32 v1, 3, v228
	v_lshlrev_b32_e32 v1, 2, v1
	s_lshl_b32 s0, s38, 2
	s_add_i32 s0, s43, s0
	v_add_u32_e32 v1, s0, v1
	ds_write_b32 v1, v114
	ds_write_b32 v1, v118 offset:16
	s_cmp_gt_u32 s42, 61
	s_cbranch_scc1 .LBB0_2525
	s_lshl_b32 s0, s42, 5
	s_add_i32 s72, s0, s40
	s_add_i32 s52, s72, -1
	s_lshl_b64 s[0:1], s[52:53], 12
	s_mov_b32 s73, s53
	v_lshl_add_u64 v[0:1], v[86:87], 0, s[0:1]
	s_lshl_b64 s[0:1], s[72:73], 12
	global_load_ushort v40, v[0:1], off
	global_load_ushort v60, v[0:1], off offset:1024
	global_load_ushort v61, v[0:1], off offset:2048
	v_lshl_add_u64 v[0:1], v[86:87], 0, s[0:1]
	s_lshl_b32 s52, s72, 12
	global_load_ushort v41, v[0:1], off
	global_load_ushort v42, v[0:1], off offset:1024
	global_load_ushort v62, v[0:1], off offset:2048
	v_lshl_add_u64 v[0:1], v[86:87], 0, s[52:53]
	v_add_co_u32_e32 v2, vcc, s66, v0
	s_movk_i32 s51, 0x3000
	s_nop 0
	v_addc_co_u32_e32 v3, vcc, 0, v1, vcc
	v_add_co_u32_e32 v6, vcc, s67, v0
	s_movk_i32 s50, 0x4000
	s_nop 0
	v_addc_co_u32_e32 v7, vcc, 0, v1, vcc
	global_load_ushort v43, v[6:7], off offset:-4096
	global_load_ushort v44, v[2:3], off offset:1024
	global_load_ushort v63, v[2:3], off offset:2048
	global_load_ushort v45, v[6:7], off
	global_load_ushort v46, v[6:7], off offset:1024
	global_load_ushort v64, v[6:7], off offset:2048
	v_add_co_u32_e32 v2, vcc, s51, v0
	s_movk_i32 s52, 0x5000
	s_nop 0
	v_addc_co_u32_e32 v3, vcc, 0, v1, vcc
	v_add_co_u32_e32 v6, vcc, s50, v0
	s_movk_i32 s0, 0x6000
	s_nop 0
	v_addc_co_u32_e32 v7, vcc, 0, v1, vcc
	global_load_ushort v47, v[6:7], off offset:-4096
	global_load_ushort v48, v[2:3], off offset:1024
	global_load_ushort v49, v[2:3], off offset:2048
	global_load_ushort v50, v[6:7], off
	global_load_ushort v51, v[6:7], off offset:1024
	global_load_ushort v52, v[6:7], off offset:2048
	v_add_co_u32_e32 v2, vcc, s52, v0
	s_movk_i32 s68, 0x5000
	s_nop 0
	v_addc_co_u32_e32 v3, vcc, 0, v1, vcc
	v_add_co_u32_e32 v6, vcc, s0, v0
	s_movk_i32 s0, 0x7000
	s_nop 0
	v_addc_co_u32_e32 v7, vcc, 0, v1, vcc
	global_load_ushort v53, v[6:7], off offset:-4096
	global_load_ushort v54, v[2:3], off offset:1024
	global_load_ushort v55, v[2:3], off offset:2048
	global_load_ushort v56, v[6:7], off
	global_load_ushort v57, v[6:7], off offset:1024
	global_load_ushort v58, v[6:7], off offset:2048
	v_add_co_u32_e32 v2, vcc, s0, v0
	s_add_u32 s0, s84, s72
	s_addc_u32 s1, s85, 0
	v_addc_co_u32_e32 v3, vcc, 0, v1, vcc
	s_mul_i32 s43, s1, 0xc00
	v_mad_u64_u32 v[16:17], s[0:1], s0, v236, v[88:89]
	v_add_u32_e32 v17, s43, v17
	v_add_co_u32_e32 v10, vcc, s66, v16
	global_load_ushort v176, v[2:3], off
	global_load_ushort v214, v[2:3], off offset:1024
	s_nop 0
	global_load_ushort v219, v[2:3], off offset:2048
	v_addc_co_u32_e32 v11, vcc, 0, v17, vcc
	v_add_co_u32_e32 v18, vcc, s67, v16
	global_load_ushort v205, v[16:17], off
	global_load_ushort v197, v[16:17], off offset:1024
	global_load_ushort v177, v[16:17], off offset:2048
	global_load_ushort v206, v[16:17], off offset:3072
	v_addc_co_u32_e32 v19, vcc, 0, v17, vcc
	global_load_ushort v198, v[18:19], off offset:-4096
	global_load_ushort v190, v[10:11], off offset:1024
	global_load_ushort v207, v[10:11], off offset:2048
	global_load_ushort v199, v[10:11], off offset:3072
	s_nop 0
	global_load_ushort v191, v[18:19], off
	global_load_ushort v208, v[18:19], off offset:1024
	global_load_ushort v200, v[18:19], off offset:2048
	global_load_ushort v192, v[18:19], off offset:3072
	v_add_co_u32_e32 v18, vcc, s51, v16
	v_addc_co_u32_e32 v19, vcc, 0, v17, vcc
	v_add_co_u32_e32 v22, vcc, s50, v16
	s_nop 0
	v_addc_co_u32_e32 v23, vcc, 0, v17, vcc
	global_load_ushort v209, v[22:23], off offset:-4096
	global_load_ushort v201, v[18:19], off offset:1024
	global_load_ushort v193, v[18:19], off offset:2048
	global_load_ushort v210, v[18:19], off offset:3072
	global_load_ushort v202, v[22:23], off
	global_load_ushort v194, v[22:23], off offset:1024
	global_load_ushort v211, v[22:23], off offset:2048
	global_load_ushort v203, v[22:23], off offset:3072
	v_add_co_u32_e32 v16, vcc, s52, v16
	v_addc_co_u32_e32 v17, vcc, 0, v17, vcc
	global_load_ushort v195, v[16:17], off
	global_load_ushort v212, v[16:17], off offset:1024
	global_load_ushort v204, v[16:17], off offset:2048
	global_load_ushort v196, v[16:17], off offset:3072
